# P4 reads A from channel-major UT via swizzled k-major LDS image + ds_read_b64_tr_b16 (P3 transpose phase and SEAM3 removed)
# speedup vs baseline: 1.0198x; 1.0134x over previous
; #define REP(k) for (int rep_ = 0; rep_ < ((PROBE_DOUBLE) == (k) ? 2 : 1); ++rep_)
; #define SEAM(k) do { if (IN(k) && IN((k) + 1)) xcd_barrier(xbar); } while (0)
;     __host__ __device__ bool next(int i, Unit& u) const {
;         const long L = (long)i * G + c; if (L >= nwg) return false;
;         int wgid = (int)L; { const int q = nwg / NXCD, r = nwg % NXCD, xcd = wgid % NXCD, off = wgid / NXCD; wgid = (xcd < r ? xcd * (q + 1) : r * (q + 1) + (xcd - r) * q) + off; }
;         const int nig = WGM * nN, gid = wgid / nig, fm = gid * WGM, gsz = (nM - fm) < WGM ? (nM - fm) : WGM;
;         u.pm = fm + ((wgid % nig) % gsz); u.pn = (wgid % nig) / gsz; return true;
; __global__ void __launch_bounds__(512) fwd_kernel(Args args) {
;     ...
;     if (IN(3)) REP(3) transpose_ut_phase(F, UT, U);
;     SEAM(3);
;     if (IN(4)) { pg8::Gemm g{U, Whout, MTOK, 1024, 1024}; pg8::StaticOrder S; S.init(MTOK, 1024, F.G, F.bid);
.LBB0_401:
	s_or_b64 exec, exec, s[4:5]
	s_waitcnt lgkmcnt(0)
	s_barrier
.LBB0_402:
	s_cmp_gt_i32 s73, 4
	s_cselect_b64 s[0:1], -1, 0
.LBB0_460:
	s_cmp_lt_i32 s72, 5
	s_cselect_b64 s[4:5], -1, 0
	s_and_b64 s[12:13], s[4:5], s[0:1]
	s_andn2_b64 vcc, exec, s[12:13]
	s_cbranch_vccnz .LBB0_511
	s_cmpk_lt_i32 s2, 0x200
	s_cselect_b64 s[0:1], -1, 0
	s_cmpk_gt_i32 s2, 0x1ff
	v_readfirstlane_b32 s10, v221
	s_cbranch_scc1 .LBB0_467
	s_ashr_i32 s3, s2, 31
	s_lshr_b32 s3, s3, 29
	s_add_i32 s3, s2, s3
	s_and_b32 s4, s3, -8
	s_sub_i32 s6, s2, s4
	s_cmp_gt_i32 s6, -1
	s_cbranch_scc0 .LBB0_464
	s_lshl_b32 s7, s6, 6
	s_cbranch_execz .LBB0_465
	s_branch .LBB0_466

; #define PG8_STAGE(bufoff, gbase, voff) do { _Pragma("unroll") for (int _i = 0; _i < 2; ++_i) \
;         __builtin_amdgcn_global_load_lds((const unsigned*)((const char*)(gbase) + (voff)[_i]), (PG8_LAS unsigned*)(lds + (bufoff) + ldsw + _i * 8192), 16, 0, 0); } while (0)
; #define PG8_WAIT_V(n) asm volatile("s_waitcnt vmcnt(" #n ")" ::: "memory")
; #define PG8_BAR __builtin_amdgcn_s_barrier()
; template <class Epi, class Sched, bool ALIGN_EPI = false, bool SP2 = false>
; __device__ __forceinline__ void gemm_phase(PG8_LAS unsigned char* lds, const Gemm g, const Sched& S, const Epi& E) {
;     ...
;     for (int i = 0; i < 2; ++i) { int R, C; stage_rc(tid * 16 + i * 8192, R, C); const int Rb = Epi::PERM ? ((R & ~31) + perm32(R & 31)) : R;
;         voffA[i] = (unsigned)(R * K + C) * 2u; voffB[i] = (unsigned)(Rb * K + C) * 2u; }
;     const size_t kstep = (size_t)(BK * 2);
;     const size_t hstep = (size_t)HALF * K * 2;
;     const size_t tstep = 2 * hstep;
;     const unsigned ldsw = (unsigned)wid * 1024u;
;     const int aoff = lds_byte(wr * 64 + fr, fq * 8), boff = lds_byte(wc * 32 + fr, fq * 8);
;     ...
;     const char* cA = (const char*)g.A + (size_t)cur.pm * tstep; const char* cB = (const char*)g.Bt + (size_t)cur.pn * tstep;
;     S.a_ready(cur);
;     if constexpr (SP2) {
;         PG8_STAGE(PG8_SB(0, 0), cB, voffB); PG8_STAGE(PG8_SB(0, 1), cB + hstep, voffB); PG8_STAGE(PG8_SA(0, 0), cA, voffA); PG8_STAGE(PG8_SA(0, 1), cA + hstep, voffA);
;         if (wr == 1) PG8_BAR;
;         PG8_WAIT_V(2); PG8_BAR;
;         PG8_STAGE(PG8_SB(1, 0), cB + kstep, voffB); PG8_STAGE(PG8_SA(1, 0), cA + kstep, voffA); PG8_STAGE(PG8_SB(1, 1), cB + hstep + kstep, voffB);
;         PG8_WAIT_V(6); PG8_BAR;
;     } else {
;         PG8_STAGE(PG8_SB(0, 0), cB, voffB); PG8_STAGE(PG8_SA(0, 0), cA, voffA); PG8_STAGE(PG8_SB(0, 1), cB + hstep, voffB); PG8_STAGE(PG8_SA(0, 1), cA + hstep, voffA);
;         if (wr == 1) PG8_BAR;
;         PG8_WAIT_V(4); PG8_BAR;
;         PG8_STAGE(PG8_SB(1, 0), cB + kstep, voffB); PG8_STAGE(PG8_SA(1, 0), cA + kstep, voffA); PG8_STAGE(PG8_SB(1, 1), cB + hstep + kstep, voffB);
;         PG8_WAIT_V(6); PG8_BAR;
;     }
.LBB0_467:
	s_andn2_b64 vcc, exec, s[0:1]
	s_cbranch_vccnz .LBB0_511
	s_mov_b32 s98, 0x400000
	s_mov_b32 s99, 0
	v_lshrrev_b32_e32 v252, 4, v221
	v_and_b32_e32 v253, 3, v252
	v_bfe_u32 v255, v252, 3, 1
	v_lshl_or_b32 v253, v255, 2, v253
	v_bfe_u32 v255, v221, 1, 3
	v_xor_b32_e32 v253, v253, v255
	v_and_b32_e32 v255, 1, v221
	v_lshl_or_b32 v253, v253, 1, v255
	v_lshlrev_b32_e32 v253, 4, v253
	v_lshl_or_b32 v252, v252, 16, v253
	v_add_u32_e32 v253, 0x200000, v252
	v_bfe_u32 v249, v221, 4, 2
	v_bfe_u32 v250, v221, 2, 2
	v_lshl_or_b32 v251, v249, 3, v250
	v_lshlrev_b32_e32 v251, 8, v251
	v_lshrrev_b32_e32 v254, 8, v221
	v_xor_b32_e32 v254, v254, v249
	v_and_b32_e32 v254, 1, v254
	v_lshl_or_b32 v251, v254, 7, v251
	v_lshl_or_b32 v251, v250, 5, v251
	v_and_b32_e32 v254, 3, v221
	v_lshl_or_b32 v249, v254, 3, v251
	v_xor_b32_e32 v250, 32, v249
	v_xor_b32_e32 v251, 64, v249
	v_xor_b32_e32 v254, 0x60, v249
	v_lshrrev_b32_e32 v2, 1, v221
	v_lshrrev_b32_e32 v3, 5, v221
	v_and_b32_e32 v2, 24, v2
	v_and_b32_e32 v3, 4, v3
	v_bfe_u32 v4, v221, 2, 2
	v_lshlrev_b32_e32 v0, 4, v221
	v_and_b32_e32 v1, 32, v221
	v_bfe_u32 v10, v221, 2, 4
	v_or3_b32 v2, v3, v4, v2
	v_lshrrev_b32_e32 v3, 3, v221
	s_movk_i32 s0, 0x70
	v_bitop3_b32 v8, v0, v1, 48 bitop3:0x6c
	v_and_b32_e32 v9, 64, v221
	v_and_or_b32 v4, v3, s0, v10
	s_movk_i32 s0, 0x60
	v_add_u32_e32 v11, 0x2000, v0
	v_or_b32_e32 v1, v8, v9
	v_and_or_b32 v3, v3, s0, v2
	v_lshrrev_b32_e32 v0, 7, v11
	s_movk_i32 s0, 0xf0
	s_lshr_b32 s1, s10, 6
	v_lshl_or_b32 v194, v3, 11, v1
	v_and_or_b32 v3, v0, s0, v10
	s_movk_i32 s0, 0xe0
	s_ashr_i32 s53, s52, 31
	s_ashr_i32 s15, s14, 31
	v_and_or_b32 v0, v0, s0, v2
	s_lshr_b32 s0, s10, 8
	s_lshl_b32 s3, s1, 10
	s_lshl_b64 s[4:5], s[52:53], 9
	s_lshl_b64 s[6:7], s[14:15], 19
	s_add_u32 s6, s28, s6
	s_addc_u32 s7, s29, s7
	s_add_i32 s33, s3, 0
	s_add_i32 m0, s33, 0x10000
	v_lshl_or_b32 v198, v0, 11, v1
	global_load_lds_dwordx4 v194, s[6:7]
	s_add_i32 m0, s33, 0x12000
	s_add_u32 s8, s6, 0x40000
	global_load_lds_dwordx4 v198, s[6:7]
	s_addc_u32 s9, s7, 0
	s_add_i32 m0, s33, 0x14000
	v_mov_b32_e32 v192, v252
	global_load_lds_dwordx4 v194, s[8:9]
	s_add_i32 m0, s33, 0x16000
	v_mov_b32_e32 v196, v253
	global_load_lds_dwordx4 v198, s[8:9]
	s_add_u32 s8, s70, s4
	s_addc_u32 s9, s71, s5
	s_add_u32 s8, s8, 0x18000000
	s_addc_u32 s9, s9, 0
	s_add_i32 s53, s33, 0x2000
	s_mov_b32 m0, s33
	s_add_u32 s4, s8, 0x100
	global_load_lds_dwordx4 v192, s[8:9]
	s_mov_b32 m0, s53
	s_addc_u32 s5, s9, 0
	s_add_i32 s54, s33, 0x4000
	global_load_lds_dwordx4 v196, s[8:9]
	s_mov_b32 m0, s54
	s_add_i32 s55, s33, 0x6000
	global_load_lds_dwordx4 v192, s[4:5]
	s_mov_b32 m0, s55
	v_mov_b32_e32 v195, 0
	global_load_lds_dwordx4 v196, s[4:5]
	v_mov_b32_e32 v199, v195
	v_mov_b32_e32 v193, v195
	v_mov_b32_e32 v197, v195
	s_cmp_eq_u32 s0, 1
	s_mov_b32 s15, 0
	v_lshl_add_u64 v[6:7], s[6:7], 0, v[194:195]
	v_lshl_add_u64 v[4:5], s[6:7], 0, v[198:199]
	v_lshl_add_u64 v[0:1], s[8:9], 0, v[192:193]
	s_cselect_b64 s[16:17], -1, 0
	s_cmp_lg_u32 s0, 1
	v_lshl_add_u64 v[2:3], s[8:9], 0, v[196:197]
	s_cbranch_scc1 .LBB0_470
	s_barrier
.LBB0_470:
	s_mov_b64 s[20:21], 0x80
	s_and_b32 s56, s1, 3
	s_add_i32 m0, s33, 0x18000
	v_lshl_add_u64 v[6:7], v[6:7], 0, s[20:21]
	s_lshl_b32 s1, s0, 13
	s_lshl_b32 s11, s56, 12
	s_waitcnt vmcnt(2)
	s_barrier
	global_load_lds_dwordx4 v[6:7], off
	v_lshl_add_u64 v[4:5], v[4:5], 0, s[20:21]
	s_add_i32 m0, s33, 0x1a000
	s_add_i32 s57, s33, 0x8000
	s_add_i32 s58, s33, 0xa000
	global_load_lds_dwordx4 v[4:5], off
	v_lshl_add_u64 v[0:1], v[0:1], 0, s[98:99]
	s_mov_b32 m0, s57
	s_add_u32 s4, s6, 0x40080
	global_load_lds_dwordx4 v[0:1], off
	v_lshl_add_u64 v[0:1], v[2:3], 0, s[98:99]
	s_mov_b32 m0, s58
	s_addc_u32 s5, s7, 0
	global_load_lds_dwordx4 v[0:1], off
	s_add_i32 m0, s33, 0x1c000
	v_lshl_add_u64 v[0:1], s[4:5], 0, v[194:195]
	global_load_lds_dwordx4 v[0:1], off
	v_lshl_add_u64 v[0:1], s[4:5], 0, v[198:199]
	s_add_i32 m0, s33, 0x1e000
	v_lshlrev_b32_e32 v4, 2, v221
	global_load_lds_dwordx4 v[0:1], off
	v_bfe_u32 v1, v221, 4, 2
	v_and_b32_e32 v0, 15, v221
	v_lshlrev_b32_e32 v3, 4, v1
	v_lshl_or_b32 v222, s0, 6, v0
	v_lshl_or_b32 v0, v0, 6, v3
	v_and_b32_e32 v4, 32, v4
	v_lshlrev_b32_e32 v5, 6, v221
	s_movk_i32 s0, 0x3c0
	v_lshlrev_b32_e32 v2, 3, v1
	v_bitop3_b32 v0, v0, s1, v4 bitop3:0xde
	v_and_or_b32 v3, v5, s0, v3
	v_cmp_eq_u32_e64 s[0:1], 0, v1
	v_lshlrev_b32_e32 v1, 8, v221
	v_lshl_or_b32 v224, s56, 5, v2
	v_and_b32_e32 v1, 0x38000, v1
	v_lshlrev_b32_e32 v2, 11, v10
	s_cmpk_lt_u32 s10, 0x100
	v_or3_b32 v1, v8, v1, v2
	s_cselect_b64 s[26:27], -1, 0
	s_ashr_i32 s59, s74, 31
	s_ashr_i32 s61, s2, 31
	v_mov_b32_e32 v200, v252
	v_lshlrev_b32_e32 v1, 4, v11
	s_waitcnt vmcnt(6)
	s_cmp_lg_u64 s[18:19], 0
	v_and_b32_e32 v1, 0x78000, v1
	v_bitop3_b32 v223, s11, v3, v4 bitop3:0xf6
	s_cselect_b64 s[30:31], -1, 0
	v_or3_b32 v1, v8, v1, v2
	s_add_i32 s62, 0, 0x10000
	s_add_i32 s63, 0, 0x14000
	v_add_u32_e32 v227, 0, v0
	v_mbcnt_lo_u32_b32 v0, -1, 0
	s_mov_b32 s60, s74
	v_mov_b32_e32 v201, v195
	v_mov_b32_e32 v202, v253
	v_mov_b32_e32 v203, v195
	v_mov_b64_e32 v[204:205], 0x200
	v_mov_b64_e32 v[206:207], 0x1ff
	v_add_u32_e32 v225, s62, v223
	v_add_u32_e32 v226, s63, v223
	v_mbcnt_hi_u32_b32 v228, -1, v0
	s_mov_b32 s64, 0
	s_barrier
	s_branch .LBB0_473

; #define PG8_STAGE(bufoff, gbase, voff) do { _Pragma("unroll") for (int _i = 0; _i < 2; ++_i) \
;         __builtin_amdgcn_global_load_lds((const unsigned*)((const char*)(gbase) + (voff)[_i]), (PG8_LAS unsigned*)(lds + (bufoff) + ldsw + _i * 8192), 16, 0, 0); } while (0)
; #define PG8_LDA(dst, b, h) do { _Pragma("unroll") for (int m = 0; m < 4; ++m) _Pragma("unroll") for (int k = 0; k < 2; ++k) dst[m][k] = *(const PG8_LAS bf16x8*)(lds + PG8_SA(b, h) + aoff + m * 2048 + k * 1024); } while (0)
; #define PG8_LDB(dst, b, h) do { _Pragma("unroll") for (int n = 0; n < 2; ++n) _Pragma("unroll") for (int k = 0; k < 2; ++k) dst[n][k] = *(const PG8_LAS bf16x8*)(lds + PG8_SB(b, h) + boff + n * 2048 + k * 1024); } while (0)
; #define PG8_SCHED __builtin_amdgcn_sched_barrier(0)
; template <class Epi, class Sched, bool ALIGN_EPI = false, bool SP2 = false>
; __device__ __forceinline__ void gemm_phase(PG8_LAS unsigned char* lds, const Gemm g, const Sched& S, const Epi& E) {
;     ...
;         const char* nA = has_next ? (const char*)g.A + (size_t)nxt.pm * tstep : cA; const char* nB = has_next ? (const char*)g.Bt + (size_t)nxt.pn * tstep : cB;
;         for (int t = 0; t < nt; t += 2) {
;             const bool last = (t == nt - 2);
;             const char* a1 = cA + (size_t)(t + 1) * kstep;
;             const char* a2 = last ? nA : cA + (size_t)(t + 2) * kstep; const char* b2 = last ? nB : cB + (size_t)(t + 2) * kstep;
;             const char* a3 = a2 + kstep; const char* b3 = b2 + kstep;
;             if (last && has_next) S.a_ready(nxt);
;             if constexpr (SP2) {
;             PG8_LDB(B0, 0, 0); PG8_LDB(B1, 0, 1); PG8_SCHED; PG8_LDA(At, 0, 0); PG8_STAGE(PG8_SA(1, 1), a1 + hstep, voffA);
;     ...
; #pragma unroll
;         for (int a = 0; a < 2; ++a)
; #pragma unroll
;             for (int b = 0; b < 2; ++b)
; #pragma unroll
;                 for (int m = 0; m < 4; ++m)
; #pragma unroll
;                     for (int n = 0; n < 2; ++n) acc[a][b][m][n] = (f32x4){0.f, 0.f, 0.f, 0.f};
;         cur = nxt; cA = nA; cB = nB; ++ui;
.LBB0_479:
	s_ashr_i32 s47, s46, 31
	s_lshl_b64 s[10:11], s[46:47], 9
	s_add_u32 s48, s70, s10
	s_addc_u32 s49, s71, s11
	s_add_u32 s48, s48, 0x18000000
	s_addc_u32 s49, s49, 0
	s_and_b64 s[10:11], s[4:5], exec
	s_cselect_b32 s47, s49, s9
	s_cselect_b32 s65, s48, s8
	s_ashr_i32 s35, s34, 31
	s_lshl_b64 s[10:11], s[34:35], 19
	s_add_u32 s50, s28, s10
	s_addc_u32 s51, s29, s11
	s_and_b64 s[10:11], s[4:5], exec
	s_cselect_b32 s35, s51, s7
	s_cselect_b32 s66, s50, s6
	s_add_u32 s8, s8, 0x400100
	s_addc_u32 s9, s9, 0
	s_add_u32 s67, s6, 0x100
	v_mov_b32_e32 v0, 0
	s_addc_u32 s76, s7, 0
	s_mov_b32 s77, -2
	s_waitcnt lgkmcnt(0)
	v_mov_b32_e32 v1, v0
	v_mov_b32_e32 v2, v0
	v_mov_b32_e32 v3, v0
	v_mov_b32_e32 v4, v0
	v_mov_b32_e32 v5, v0
	v_mov_b32_e32 v6, v0
	v_mov_b32_e32 v7, v0
	v_mov_b32_e32 v16, v0
	v_mov_b32_e32 v17, v0
	v_mov_b32_e32 v18, v0
	v_mov_b32_e32 v19, v0
	v_mov_b32_e32 v20, v0
	v_mov_b32_e32 v21, v0
	v_mov_b32_e32 v22, v0
	v_mov_b32_e32 v23, v0
	v_mov_b32_e32 v32, v0
	v_mov_b32_e32 v33, v0
	v_mov_b32_e32 v34, v0
	v_mov_b32_e32 v35, v0
	v_mov_b32_e32 v36, v0
	v_mov_b32_e32 v37, v0
	v_mov_b32_e32 v38, v0
	v_mov_b32_e32 v39, v0
	v_mov_b32_e32 v48, v0
	v_mov_b32_e32 v49, v0
	v_mov_b32_e32 v50, v0
	v_mov_b32_e32 v51, v0
	v_mov_b32_e32 v52, v0
	v_mov_b32_e32 v53, v0
	v_mov_b32_e32 v54, v0
	v_mov_b32_e32 v55, v0
	v_mov_b32_e32 v8, v0
	v_mov_b32_e32 v9, v0
	v_mov_b32_e32 v10, v0
	v_mov_b32_e32 v11, v0
	v_mov_b32_e32 v12, v0
	v_mov_b32_e32 v13, v0
	v_mov_b32_e32 v14, v0
	v_mov_b32_e32 v15, v0
	v_mov_b32_e32 v24, v0
	v_mov_b32_e32 v25, v0
	v_mov_b32_e32 v26, v0
	v_mov_b32_e32 v27, v0
	v_mov_b32_e32 v28, v0
	v_mov_b32_e32 v29, v0
	v_mov_b32_e32 v30, v0
	v_mov_b32_e32 v31, v0
	v_mov_b32_e32 v40, v0
	v_mov_b32_e32 v41, v0
	v_mov_b32_e32 v42, v0
	v_mov_b32_e32 v43, v0
	v_mov_b32_e32 v44, v0
	v_mov_b32_e32 v45, v0
	v_mov_b32_e32 v46, v0
	v_mov_b32_e32 v47, v0
	v_mov_b32_e32 v56, v0
	v_mov_b32_e32 v57, v0
	v_mov_b32_e32 v58, v0
	v_mov_b32_e32 v59, v0
	v_mov_b32_e32 v60, v0
	v_mov_b32_e32 v61, v0
	v_mov_b32_e32 v62, v0
	v_mov_b32_e32 v63, v0
	v_mov_b32_e32 v64, v0
	v_mov_b32_e32 v65, v0
	v_mov_b32_e32 v66, v0
	v_mov_b32_e32 v67, v0
	v_mov_b32_e32 v68, v0
	v_mov_b32_e32 v69, v0
	v_mov_b32_e32 v70, v0
	v_mov_b32_e32 v71, v0
	v_mov_b32_e32 v80, v0
	v_mov_b32_e32 v81, v0
	v_mov_b32_e32 v82, v0
	v_mov_b32_e32 v83, v0
	v_mov_b32_e32 v84, v0
	v_mov_b32_e32 v85, v0
	v_mov_b32_e32 v86, v0
	v_mov_b32_e32 v87, v0
	v_mov_b32_e32 v112, v0
	v_mov_b32_e32 v113, v0
	v_mov_b32_e32 v114, v0
	v_mov_b32_e32 v115, v0
	v_mov_b32_e32 v116, v0
	v_mov_b32_e32 v117, v0
	v_mov_b32_e32 v118, v0
	v_mov_b32_e32 v119, v0
	v_mov_b32_e32 v128, v0
	v_mov_b32_e32 v129, v0
	v_mov_b32_e32 v130, v0
	v_mov_b32_e32 v131, v0
	v_mov_b32_e32 v132, v0
	v_mov_b32_e32 v133, v0
	v_mov_b32_e32 v134, v0
	v_mov_b32_e32 v135, v0
	v_mov_b32_e32 v72, v0
	v_mov_b32_e32 v73, v0
	v_mov_b32_e32 v74, v0
	v_mov_b32_e32 v75, v0
	v_mov_b32_e32 v76, v0
	v_mov_b32_e32 v77, v0
	v_mov_b32_e32 v78, v0
	v_mov_b32_e32 v79, v0
	v_mov_b32_e32 v100, v0
	v_mov_b32_e32 v101, v0
	v_mov_b32_e32 v102, v0
	v_mov_b32_e32 v103, v0
	v_mov_b32_e32 v108, v0
	v_mov_b32_e32 v109, v0
	v_mov_b32_e32 v110, v0
	v_mov_b32_e32 v111, v0
	v_mov_b32_e32 v120, v0
	v_mov_b32_e32 v121, v0
	v_mov_b32_e32 v122, v0
	v_mov_b32_e32 v123, v0
	v_mov_b32_e32 v124, v0
	v_mov_b32_e32 v125, v0
	v_mov_b32_e32 v126, v0
	v_mov_b32_e32 v127, v0
	v_mov_b32_e32 v136, v0
	v_mov_b32_e32 v137, v0
	v_mov_b32_e32 v138, v0
	v_mov_b32_e32 v139, v0
	v_mov_b32_e32 v140, v0
	v_mov_b32_e32 v141, v0
	v_mov_b32_e32 v142, v0
	v_mov_b32_e32 v143, v0
.LBB0_480:
	ds_read_b128 v[88:91], v225
	ds_read_b128 v[92:95], v225 offset:1024
	ds_read_b128 v[96:99], v225 offset:2048
	ds_read_b128 v[104:107], v225 offset:3072
	ds_read_b128 v[144:147], v226
	ds_read_b128 v[148:151], v226 offset:1024
	ds_read_b128 v[152:155], v226 offset:2048
	ds_read_b128 v[156:159], v226 offset:3072
	s_add_u32 s6, s8, 0x3fff00
	s_addc_u32 s7, s9, 0
	s_cmp_eq_u32 s77, 12
	s_cselect_b32 s11, s47, s7
	s_cselect_b32 s10, s65, s6
	s_cselect_b32 s7, s35, s76
	s_cselect_b32 s6, s66, s67
	v_lshl_add_u64 v[208:209], s[8:9], 0, v[200:201]
	s_add_i32 m0, s33, 0xc000
	ds_read_b64_tr_b16 v[160:161], v249
	ds_read_b64_tr_b16 v[162:163], v249 offset:1024
	ds_read_b64_tr_b16 v[164:165], v249 offset:8192
	ds_read_b64_tr_b16 v[166:167], v249 offset:9216
	ds_read_b64_tr_b16 v[168:169], v250
	ds_read_b64_tr_b16 v[170:171], v250 offset:1024
	ds_read_b64_tr_b16 v[172:173], v250 offset:8192
	ds_read_b64_tr_b16 v[174:175], v250 offset:9216
	ds_read_b64_tr_b16 v[176:177], v251
	ds_read_b64_tr_b16 v[178:179], v251 offset:1024
	ds_read_b64_tr_b16 v[180:181], v251 offset:8192
	ds_read_b64_tr_b16 v[182:183], v251 offset:9216
	ds_read_b64_tr_b16 v[184:185], v254
	ds_read_b64_tr_b16 v[186:187], v254 offset:1024
	ds_read_b64_tr_b16 v[188:189], v254 offset:8192
	ds_read_b64_tr_b16 v[190:191], v254 offset:9216
	global_load_lds_dwordx4 v[208:209], off
	v_lshl_add_u64 v[208:209], s[8:9], 0, v[202:203]
	s_add_i32 m0, s33, 0xe000
	s_nop 0
	global_load_lds_dwordx4 v[208:209], off
	s_waitcnt vmcnt(8)
	s_waitcnt lgkmcnt(0)
	s_barrier
; #define PG8_STAGE(bufoff, gbase, voff) do { _Pragma("unroll") for (int _i = 0; _i < 2; ++_i) \
;         __builtin_amdgcn_global_load_lds((const unsigned*)((const char*)(gbase) + (voff)[_i]), (PG8_LAS unsigned*)(lds + (bufoff) + ldsw + _i * 8192), 16, 0, 0); } while (0)
; #define PG8_LDA(dst, b, h) do { _Pragma("unroll") for (int m = 0; m < 4; ++m) _Pragma("unroll") for (int k = 0; k < 2; ++k) dst[m][k] = *(const PG8_LAS bf16x8*)(lds + PG8_SA(b, h) + aoff + m * 2048 + k * 1024); } while (0)
; #define PG8_MMA(ai, bj, At, Bt) do { __builtin_amdgcn_s_setprio(1); _Pragma("unroll") for (int m = 0; m < 4; ++m) _Pragma("unroll") for (int n = 0; n < 2; ++n) _Pragma("unroll") for (int k = 0; k < 2; ++k) \
;         acc[ai][bj][m][n] = __builtin_amdgcn_mfma_f32_16x16x32_bf16(Bt[n][k], At[m][k], acc[ai][bj][m][n], 0, 0, 0); __builtin_amdgcn_s_setprio(0); } while (0)
; #define PG8_WAIT_V(n) asm volatile("s_waitcnt vmcnt(" #n ")" ::: "memory")
; #define PG8_WAIT_L(n) asm volatile("s_waitcnt lgkmcnt(" #n ")" ::: "memory")
; #define PG8_BAR __builtin_amdgcn_s_barrier()
; #define PG8_SCHED __builtin_amdgcn_sched_barrier(0)
; template <class Epi, class Sched, bool ALIGN_EPI = false, bool SP2 = false>
; __device__ __forceinline__ void gemm_phase(PG8_LAS unsigned char* lds, const Gemm g, const Sched& S, const Epi& E) {
;     ...
;             PG8_WAIT_V(8); PG8_WAIT_L(0); PG8_BAR; PG8_MMA(0, 0, At, B0); PG8_MMA(0, 1, At, B1); PG8_BAR; PG8_SCHED;
;             PG8_LDA(At, 0, 1); PG8_STAGE(PG8_SB(0, 0), b2, voffB); PG8_STAGE(PG8_SB(0, 1), b2 + hstep, voffB); PG8_STAGE(PG8_SA(0, 0), a2, voffA);
;             PG8_WAIT_V(8); PG8_WAIT_L(0); PG8_BAR; PG8_MMA(1, 0, At, B0); PG8_MMA(1, 1, At, B1); PG8_BAR; PG8_SCHED;
	s_waitcnt lgkmcnt(0)
	v_mfma_f32_16x16x32_bf16 v[140:143], v[88:91], v[160:163], v[140:143]
	v_mfma_f32_16x16x32_bf16 v[136:139], v[96:99], v[160:163], v[136:139]
	v_mfma_f32_16x16x32_bf16 v[124:127], v[88:91], v[168:171], v[124:127]
	v_mfma_f32_16x16x32_bf16 v[120:123], v[96:99], v[168:171], v[120:123]
	v_mfma_f32_16x16x32_bf16 v[108:111], v[88:91], v[176:179], v[108:111]
	v_mfma_f32_16x16x32_bf16 v[100:103], v[96:99], v[176:179], v[100:103]
	v_mfma_f32_16x16x32_bf16 v[76:79], v[88:91], v[184:187], v[76:79]
	v_mfma_f32_16x16x32_bf16 v[72:75], v[96:99], v[184:187], v[72:75]
	v_mfma_f32_16x16x32_bf16 v[140:143], v[92:95], v[164:167], v[140:143]
	v_mfma_f32_16x16x32_bf16 v[136:139], v[104:107], v[164:167], v[136:139]
	v_mfma_f32_16x16x32_bf16 v[124:127], v[92:95], v[172:175], v[124:127]
	v_mfma_f32_16x16x32_bf16 v[120:123], v[104:107], v[172:175], v[120:123]
	v_mfma_f32_16x16x32_bf16 v[108:111], v[92:95], v[180:183], v[108:111]
	v_mfma_f32_16x16x32_bf16 v[100:103], v[104:107], v[180:183], v[100:103]
	v_mfma_f32_16x16x32_bf16 v[76:79], v[92:95], v[188:191], v[76:79]
	v_mfma_f32_16x16x32_bf16 v[72:75], v[104:107], v[188:191], v[72:75]
	v_mfma_f32_16x16x32_bf16 v[132:135], v[144:147], v[160:163], v[132:135]
	v_mfma_f32_16x16x32_bf16 v[128:131], v[152:155], v[160:163], v[128:131]
	v_mfma_f32_16x16x32_bf16 v[116:119], v[144:147], v[168:171], v[116:119]
	v_mfma_f32_16x16x32_bf16 v[112:115], v[152:155], v[168:171], v[112:115]
	v_mfma_f32_16x16x32_bf16 v[84:87], v[144:147], v[176:179], v[84:87]
	v_mfma_f32_16x16x32_bf16 v[80:83], v[152:155], v[176:179], v[80:83]
	v_mfma_f32_16x16x32_bf16 v[68:71], v[144:147], v[184:187], v[68:71]
	v_mfma_f32_16x16x32_bf16 v[64:67], v[152:155], v[184:187], v[64:67]
	v_mfma_f32_16x16x32_bf16 v[132:135], v[148:151], v[164:167], v[132:135]
	v_mfma_f32_16x16x32_bf16 v[128:131], v[156:159], v[164:167], v[128:131]
	v_mfma_f32_16x16x32_bf16 v[116:119], v[148:151], v[172:175], v[116:119]
	v_mfma_f32_16x16x32_bf16 v[112:115], v[156:159], v[172:175], v[112:115]
	v_mfma_f32_16x16x32_bf16 v[84:87], v[148:151], v[180:183], v[84:87]
	v_mfma_f32_16x16x32_bf16 v[80:83], v[156:159], v[180:183], v[80:83]
	v_mfma_f32_16x16x32_bf16 v[68:71], v[148:151], v[188:191], v[68:71]
	v_mfma_f32_16x16x32_bf16 v[64:67], v[156:159], v[188:191], v[64:67]
	s_barrier
	s_add_i32 s78, s62, s3
	v_lshl_add_u64 v[208:209], s[6:7], 0, v[194:195]
	s_mov_b32 m0, s78
	ds_read_b64_tr_b16 v[160:161], v249 offset:16384
	ds_read_b64_tr_b16 v[162:163], v249 offset:17408
	ds_read_b64_tr_b16 v[164:165], v249 offset:24576
	ds_read_b64_tr_b16 v[166:167], v249 offset:25600
	ds_read_b64_tr_b16 v[168:169], v250 offset:16384
	ds_read_b64_tr_b16 v[170:171], v250 offset:17408
	ds_read_b64_tr_b16 v[172:173], v250 offset:24576
	ds_read_b64_tr_b16 v[174:175], v250 offset:25600
	ds_read_b64_tr_b16 v[176:177], v251 offset:16384
	ds_read_b64_tr_b16 v[178:179], v251 offset:17408
	ds_read_b64_tr_b16 v[180:181], v251 offset:24576
	ds_read_b64_tr_b16 v[182:183], v251 offset:25600
	ds_read_b64_tr_b16 v[184:185], v254 offset:16384
	ds_read_b64_tr_b16 v[186:187], v254 offset:17408
	ds_read_b64_tr_b16 v[188:189], v254 offset:24576
	ds_read_b64_tr_b16 v[190:191], v254 offset:25600
	global_load_lds_dwordx4 v[208:209], off
	s_add_i32 m0, s78, 0x2000
	s_add_u32 s78, s6, 0x40000
	v_lshl_add_u64 v[210:211], s[6:7], 0, v[198:199]
	s_addc_u32 s79, s7, 0
	s_add_i32 s80, s63, s3
	global_load_lds_dwordx4 v[210:211], off
	v_lshl_add_u64 v[212:213], s[78:79], 0, v[194:195]
	s_mov_b32 m0, s80
	v_lshl_add_u64 v[214:215], s[10:11], 0, v[196:197]
	global_load_lds_dwordx4 v[212:213], off
	v_lshl_add_u64 v[212:213], s[78:79], 0, v[198:199]
	s_add_i32 m0, s80, 0x2000
	s_nop 0
	global_load_lds_dwordx4 v[212:213], off
	v_lshl_add_u64 v[212:213], s[10:11], 0, v[192:193]
	s_mov_b32 m0, s33
	s_nop 0
	global_load_lds_dwordx4 v[212:213], off
	s_mov_b32 m0, s53
	s_nop 0
	global_load_lds_dwordx4 v[214:215], off
	s_waitcnt vmcnt(8)
	s_waitcnt lgkmcnt(0)
	s_barrier
	s_waitcnt lgkmcnt(0)
	v_mfma_f32_16x16x32_bf16 v[60:63], v[88:91], v[160:163], v[60:63]
	v_mfma_f32_16x16x32_bf16 v[56:59], v[96:99], v[160:163], v[56:59]
	v_mfma_f32_16x16x32_bf16 v[44:47], v[88:91], v[168:171], v[44:47]
	v_mfma_f32_16x16x32_bf16 v[40:43], v[96:99], v[168:171], v[40:43]
	v_mfma_f32_16x16x32_bf16 v[28:31], v[88:91], v[176:179], v[28:31]
	v_mfma_f32_16x16x32_bf16 v[24:27], v[96:99], v[176:179], v[24:27]
	v_mfma_f32_16x16x32_bf16 v[12:15], v[88:91], v[184:187], v[12:15]
	v_mfma_f32_16x16x32_bf16 v[8:11], v[96:99], v[184:187], v[8:11]
	v_mfma_f32_16x16x32_bf16 v[60:63], v[92:95], v[164:167], v[60:63]
	v_mfma_f32_16x16x32_bf16 v[56:59], v[104:107], v[164:167], v[56:59]
	v_mfma_f32_16x16x32_bf16 v[44:47], v[92:95], v[172:175], v[44:47]
	v_mfma_f32_16x16x32_bf16 v[40:43], v[104:107], v[172:175], v[40:43]
	v_mfma_f32_16x16x32_bf16 v[28:31], v[92:95], v[180:183], v[28:31]
	v_mfma_f32_16x16x32_bf16 v[24:27], v[104:107], v[180:183], v[24:27]
	v_mfma_f32_16x16x32_bf16 v[12:15], v[92:95], v[188:191], v[12:15]
	v_mfma_f32_16x16x32_bf16 v[8:11], v[104:107], v[188:191], v[8:11]
	v_mfma_f32_16x16x32_bf16 v[52:55], v[144:147], v[160:163], v[52:55]
	v_mfma_f32_16x16x32_bf16 v[48:51], v[152:155], v[160:163], v[48:51]
	v_mfma_f32_16x16x32_bf16 v[36:39], v[144:147], v[168:171], v[36:39]
	v_mfma_f32_16x16x32_bf16 v[32:35], v[152:155], v[168:171], v[32:35]
	v_mfma_f32_16x16x32_bf16 v[20:23], v[144:147], v[176:179], v[20:23]
	v_mfma_f32_16x16x32_bf16 v[16:19], v[152:155], v[176:179], v[16:19]
	v_mfma_f32_16x16x32_bf16 v[4:7], v[144:147], v[184:187], v[4:7]
	v_mfma_f32_16x16x32_bf16 v[0:3], v[152:155], v[184:187], v[0:3]
	v_mfma_f32_16x16x32_bf16 v[52:55], v[148:151], v[164:167], v[52:55]
	v_mfma_f32_16x16x32_bf16 v[48:51], v[156:159], v[164:167], v[48:51]
	v_mfma_f32_16x16x32_bf16 v[36:39], v[148:151], v[172:175], v[36:39]
	v_mfma_f32_16x16x32_bf16 v[32:35], v[156:159], v[172:175], v[32:35]
	v_mfma_f32_16x16x32_bf16 v[20:23], v[148:151], v[180:183], v[20:23]
	v_mfma_f32_16x16x32_bf16 v[16:19], v[156:159], v[180:183], v[16:19]
	v_mfma_f32_16x16x32_bf16 v[4:7], v[148:151], v[188:191], v[4:7]
	v_mfma_f32_16x16x32_bf16 v[0:3], v[156:159], v[188:191], v[0:3]
	s_barrier
; #define PG8_STAGE(bufoff, gbase, voff) do { _Pragma("unroll") for (int _i = 0; _i < 2; ++_i) \
;         __builtin_amdgcn_global_load_lds((const unsigned*)((const char*)(gbase) + (voff)[_i]), (PG8_LAS unsigned*)(lds + (bufoff) + ldsw + _i * 8192), 16, 0, 0); } while (0)
; #define PG8_LDA(dst, b, h) do { _Pragma("unroll") for (int m = 0; m < 4; ++m) _Pragma("unroll") for (int k = 0; k < 2; ++k) dst[m][k] = *(const PG8_LAS bf16x8*)(lds + PG8_SA(b, h) + aoff + m * 2048 + k * 1024); } while (0)
; #define PG8_LDB(dst, b, h) do { _Pragma("unroll") for (int n = 0; n < 2; ++n) _Pragma("unroll") for (int k = 0; k < 2; ++k) dst[n][k] = *(const PG8_LAS bf16x8*)(lds + PG8_SB(b, h) + boff + n * 2048 + k * 1024); } while (0)
; #define PG8_MMA(ai, bj, At, Bt) do { __builtin_amdgcn_s_setprio(1); _Pragma("unroll") for (int m = 0; m < 4; ++m) _Pragma("unroll") for (int n = 0; n < 2; ++n) _Pragma("unroll") for (int k = 0; k < 2; ++k) \
;         acc[ai][bj][m][n] = __builtin_amdgcn_mfma_f32_16x16x32_bf16(Bt[n][k], At[m][k], acc[ai][bj][m][n], 0, 0, 0); __builtin_amdgcn_s_setprio(0); } while (0)
; #define PG8_WAIT_V(n) asm volatile("s_waitcnt vmcnt(" #n ")" ::: "memory")
; #define PG8_WAIT_L(n) asm volatile("s_waitcnt lgkmcnt(" #n ")" ::: "memory")
; #define PG8_BAR __builtin_amdgcn_s_barrier()
; #define PG8_SCHED __builtin_amdgcn_sched_barrier(0)
; template <class Epi, class Sched, bool ALIGN_EPI = false, bool SP2 = false>
; __device__ __forceinline__ void gemm_phase(PG8_LAS unsigned char* lds, const Gemm g, const Sched& S, const Epi& E) {
;     ...
;             PG8_LDB(B0, 1, 0); PG8_LDB(B1, 1, 1); PG8_SCHED; PG8_LDA(At, 1, 0); PG8_STAGE(PG8_SA(0, 1), a2 + hstep, voffA);
;             PG8_WAIT_V(8); PG8_WAIT_L(0); PG8_BAR; PG8_MMA(0, 0, At, B0); PG8_MMA(0, 1, At, B1); PG8_BAR; PG8_SCHED;
	s_add_i32 s78, 0, 0x18000
	s_add_i32 s79, 0, 0x1c000
	v_add_u32_e32 v104, s78, v223
	v_add_u32_e32 v156, s79, v223
	ds_read_b128 v[88:91], v104
	ds_read_b128 v[92:95], v104 offset:1024
	ds_read_b128 v[96:99], v104 offset:2048
	ds_read_b128 v[104:107], v104 offset:3072
	ds_read_b128 v[144:147], v156
	ds_read_b128 v[148:151], v156 offset:1024
	ds_read_b128 v[152:155], v156 offset:2048
	ds_read_b128 v[156:159], v156 offset:3072
	s_add_u32 s10, s10, 0x100
	s_addc_u32 s11, s11, 0
	s_mov_b32 m0, s54
	v_lshl_add_u64 v[216:217], s[10:11], 0, v[192:193]
	ds_read_b64_tr_b16 v[160:161], v249 offset:32768
	ds_read_b64_tr_b16 v[162:163], v249 offset:33792
	ds_read_b64_tr_b16 v[164:165], v249 offset:40960
	ds_read_b64_tr_b16 v[166:167], v249 offset:41984
	ds_read_b64_tr_b16 v[168:169], v250 offset:32768
	ds_read_b64_tr_b16 v[170:171], v250 offset:33792
	ds_read_b64_tr_b16 v[172:173], v250 offset:40960
	ds_read_b64_tr_b16 v[174:175], v250 offset:41984
	ds_read_b64_tr_b16 v[176:177], v251 offset:32768
	ds_read_b64_tr_b16 v[178:179], v251 offset:33792
	ds_read_b64_tr_b16 v[180:181], v251 offset:40960
	ds_read_b64_tr_b16 v[182:183], v251 offset:41984
	ds_read_b64_tr_b16 v[184:185], v254 offset:32768
	ds_read_b64_tr_b16 v[186:187], v254 offset:33792
	ds_read_b64_tr_b16 v[188:189], v254 offset:40960
	ds_read_b64_tr_b16 v[190:191], v254 offset:41984
	global_load_lds_dwordx4 v[216:217], off
	v_lshl_add_u64 v[216:217], s[10:11], 0, v[196:197]
	s_mov_b32 m0, s55
	s_nop 0
	global_load_lds_dwordx4 v[216:217], off
	s_waitcnt vmcnt(8)
	s_waitcnt lgkmcnt(0)
	s_barrier
	s_waitcnt lgkmcnt(0)
	v_mfma_f32_16x16x32_bf16 v[140:143], v[88:91], v[160:163], v[140:143]
	v_mfma_f32_16x16x32_bf16 v[136:139], v[96:99], v[160:163], v[136:139]
	v_mfma_f32_16x16x32_bf16 v[124:127], v[88:91], v[168:171], v[124:127]
	v_mfma_f32_16x16x32_bf16 v[120:123], v[96:99], v[168:171], v[120:123]
	v_mfma_f32_16x16x32_bf16 v[108:111], v[88:91], v[176:179], v[108:111]
	v_mfma_f32_16x16x32_bf16 v[100:103], v[96:99], v[176:179], v[100:103]
	v_mfma_f32_16x16x32_bf16 v[76:79], v[88:91], v[184:187], v[76:79]
	v_mfma_f32_16x16x32_bf16 v[72:75], v[96:99], v[184:187], v[72:75]
	v_mfma_f32_16x16x32_bf16 v[140:143], v[92:95], v[164:167], v[140:143]
	v_mfma_f32_16x16x32_bf16 v[136:139], v[104:107], v[164:167], v[136:139]
	v_mfma_f32_16x16x32_bf16 v[124:127], v[92:95], v[172:175], v[124:127]
	v_mfma_f32_16x16x32_bf16 v[120:123], v[104:107], v[172:175], v[120:123]
	v_mfma_f32_16x16x32_bf16 v[108:111], v[92:95], v[180:183], v[108:111]
	v_mfma_f32_16x16x32_bf16 v[100:103], v[104:107], v[180:183], v[100:103]
	v_mfma_f32_16x16x32_bf16 v[76:79], v[92:95], v[188:191], v[76:79]
	v_mfma_f32_16x16x32_bf16 v[72:75], v[104:107], v[188:191], v[72:75]
	v_mfma_f32_16x16x32_bf16 v[132:135], v[144:147], v[160:163], v[132:135]
	v_mfma_f32_16x16x32_bf16 v[128:131], v[152:155], v[160:163], v[128:131]
	v_mfma_f32_16x16x32_bf16 v[116:119], v[144:147], v[168:171], v[116:119]
	v_mfma_f32_16x16x32_bf16 v[112:115], v[152:155], v[168:171], v[112:115]
	v_mfma_f32_16x16x32_bf16 v[84:87], v[144:147], v[176:179], v[84:87]
	v_mfma_f32_16x16x32_bf16 v[80:83], v[152:155], v[176:179], v[80:83]
	v_mfma_f32_16x16x32_bf16 v[68:71], v[144:147], v[184:187], v[68:71]
	v_mfma_f32_16x16x32_bf16 v[64:67], v[152:155], v[184:187], v[64:67]
	v_mfma_f32_16x16x32_bf16 v[132:135], v[148:151], v[164:167], v[132:135]
	v_mfma_f32_16x16x32_bf16 v[128:131], v[156:159], v[164:167], v[128:131]
	v_mfma_f32_16x16x32_bf16 v[116:119], v[148:151], v[172:175], v[116:119]
	v_mfma_f32_16x16x32_bf16 v[112:115], v[156:159], v[172:175], v[112:115]
	v_mfma_f32_16x16x32_bf16 v[84:87], v[148:151], v[180:183], v[84:87]
	v_mfma_f32_16x16x32_bf16 v[80:83], v[156:159], v[180:183], v[80:83]
	v_mfma_f32_16x16x32_bf16 v[68:71], v[148:151], v[188:191], v[68:71]
	v_mfma_f32_16x16x32_bf16 v[64:67], v[156:159], v[188:191], v[64:67]
	s_barrier
; #define PG8_STAGE(bufoff, gbase, voff) do { _Pragma("unroll") for (int _i = 0; _i < 2; ++_i) \
;         __builtin_amdgcn_global_load_lds((const unsigned*)((const char*)(gbase) + (voff)[_i]), (PG8_LAS unsigned*)(lds + (bufoff) + ldsw + _i * 8192), 16, 0, 0); } while (0)
; #define PG8_LDA(dst, b, h) do { _Pragma("unroll") for (int m = 0; m < 4; ++m) _Pragma("unroll") for (int k = 0; k < 2; ++k) dst[m][k] = *(const PG8_LAS bf16x8*)(lds + PG8_SA(b, h) + aoff + m * 2048 + k * 1024); } while (0)
; #define PG8_MMA(ai, bj, At, Bt) do { __builtin_amdgcn_s_setprio(1); _Pragma("unroll") for (int m = 0; m < 4; ++m) _Pragma("unroll") for (int n = 0; n < 2; ++n) _Pragma("unroll") for (int k = 0; k < 2; ++k) \
;         acc[ai][bj][m][n] = __builtin_amdgcn_mfma_f32_16x16x32_bf16(Bt[n][k], At[m][k], acc[ai][bj][m][n], 0, 0, 0); __builtin_amdgcn_s_setprio(0); } while (0)
; #define PG8_WAIT_V(n) asm volatile("s_waitcnt vmcnt(" #n ")" ::: "memory")
; #define PG8_WAIT_L(n) asm volatile("s_waitcnt lgkmcnt(" #n ")" ::: "memory")
; #define PG8_BAR __builtin_amdgcn_s_barrier()
; #define PG8_SCHED __builtin_amdgcn_sched_barrier(0)
; template <class Epi, class Sched, bool ALIGN_EPI = false, bool SP2 = false>
; __device__ __forceinline__ void gemm_phase(PG8_LAS unsigned char* lds, const Gemm g, const Sched& S, const Epi& E) {
;     ...
;         for (int t = 0; t < nt; t += 2) {
;     ...
;             PG8_LDA(At, 1, 1); PG8_STAGE(PG8_SB(1, 0), b3, voffB); PG8_STAGE(PG8_SB(1, 1), b3 + hstep, voffB); PG8_STAGE(PG8_SA(1, 0), a3, voffA);
;             PG8_WAIT_V(8); PG8_WAIT_L(0); PG8_BAR; PG8_MMA(1, 0, At, B0); PG8_MMA(1, 1, At, B1); PG8_BAR; PG8_SCHED;
	s_add_i32 s10, s78, s3
	v_lshl_add_u64 v[208:209], v[208:209], 0, s[20:21]
	s_mov_b32 m0, s10
	ds_read_b64_tr_b16 v[160:161], v249 offset:49152
	ds_read_b64_tr_b16 v[162:163], v249 offset:50176
	ds_read_b64_tr_b16 v[164:165], v249 offset:57344
	ds_read_b64_tr_b16 v[166:167], v249 offset:58368
	ds_read_b64_tr_b16 v[168:169], v250 offset:49152
	ds_read_b64_tr_b16 v[170:171], v250 offset:50176
	ds_read_b64_tr_b16 v[172:173], v250 offset:57344
	ds_read_b64_tr_b16 v[174:175], v250 offset:58368
	ds_read_b64_tr_b16 v[176:177], v251 offset:49152
	ds_read_b64_tr_b16 v[178:179], v251 offset:50176
	ds_read_b64_tr_b16 v[180:181], v251 offset:57344
	ds_read_b64_tr_b16 v[182:183], v251 offset:58368
	ds_read_b64_tr_b16 v[184:185], v254 offset:49152
	ds_read_b64_tr_b16 v[186:187], v254 offset:50176
	ds_read_b64_tr_b16 v[188:189], v254 offset:57344
	ds_read_b64_tr_b16 v[190:191], v254 offset:58368
	global_load_lds_dwordx4 v[208:209], off
	s_add_i32 m0, s10, 0x2000
	s_add_u32 s6, s6, 0x40080
	v_lshl_add_u64 v[208:209], v[210:211], 0, s[20:21]
	s_addc_u32 s7, s7, 0
	s_add_i32 s10, s79, s3
	global_load_lds_dwordx4 v[208:209], off
	v_lshl_add_u64 v[208:209], s[6:7], 0, v[194:195]
	s_mov_b32 m0, s10
	s_nop 0
	global_load_lds_dwordx4 v[208:209], off
	v_lshl_add_u64 v[208:209], s[6:7], 0, v[198:199]
	s_add_i32 m0, s10, 0x2000
	s_nop 0
	global_load_lds_dwordx4 v[208:209], off
	v_lshl_add_u64 v[208:209], v[212:213], 0, s[98:99]
	s_mov_b32 m0, s57
	s_nop 0
	global_load_lds_dwordx4 v[208:209], off
	v_lshl_add_u64 v[208:209], v[214:215], 0, s[98:99]
	s_mov_b32 m0, s58
	s_nop 0
	global_load_lds_dwordx4 v[208:209], off
	s_waitcnt vmcnt(8)
	s_waitcnt lgkmcnt(0)
	s_barrier
	s_waitcnt lgkmcnt(0)
	v_mfma_f32_16x16x32_bf16 v[60:63], v[88:91], v[160:163], v[60:63]
	v_mfma_f32_16x16x32_bf16 v[56:59], v[96:99], v[160:163], v[56:59]
	v_mfma_f32_16x16x32_bf16 v[44:47], v[88:91], v[168:171], v[44:47]
	v_mfma_f32_16x16x32_bf16 v[40:43], v[96:99], v[168:171], v[40:43]
	v_mfma_f32_16x16x32_bf16 v[28:31], v[88:91], v[176:179], v[28:31]
	v_mfma_f32_16x16x32_bf16 v[24:27], v[96:99], v[176:179], v[24:27]
	v_mfma_f32_16x16x32_bf16 v[12:15], v[88:91], v[184:187], v[12:15]
	v_mfma_f32_16x16x32_bf16 v[8:11], v[96:99], v[184:187], v[8:11]
	v_mfma_f32_16x16x32_bf16 v[60:63], v[92:95], v[164:167], v[60:63]
	v_mfma_f32_16x16x32_bf16 v[56:59], v[104:107], v[164:167], v[56:59]
	v_mfma_f32_16x16x32_bf16 v[44:47], v[92:95], v[172:175], v[44:47]
	v_mfma_f32_16x16x32_bf16 v[40:43], v[104:107], v[172:175], v[40:43]
	v_mfma_f32_16x16x32_bf16 v[28:31], v[92:95], v[180:183], v[28:31]
	v_mfma_f32_16x16x32_bf16 v[24:27], v[104:107], v[180:183], v[24:27]
	v_mfma_f32_16x16x32_bf16 v[12:15], v[92:95], v[188:191], v[12:15]
	v_mfma_f32_16x16x32_bf16 v[8:11], v[104:107], v[188:191], v[8:11]
	v_mfma_f32_16x16x32_bf16 v[52:55], v[144:147], v[160:163], v[52:55]
	v_mfma_f32_16x16x32_bf16 v[48:51], v[152:155], v[160:163], v[48:51]
	v_mfma_f32_16x16x32_bf16 v[36:39], v[144:147], v[168:171], v[36:39]
	v_mfma_f32_16x16x32_bf16 v[32:35], v[152:155], v[168:171], v[32:35]
	v_mfma_f32_16x16x32_bf16 v[20:23], v[144:147], v[176:179], v[20:23]
	v_mfma_f32_16x16x32_bf16 v[16:19], v[152:155], v[176:179], v[16:19]
	v_mfma_f32_16x16x32_bf16 v[4:7], v[144:147], v[184:187], v[4:7]
	v_mfma_f32_16x16x32_bf16 v[0:3], v[152:155], v[184:187], v[0:3]
	v_mfma_f32_16x16x32_bf16 v[52:55], v[148:151], v[164:167], v[52:55]
	v_mfma_f32_16x16x32_bf16 v[48:51], v[156:159], v[164:167], v[48:51]
	v_mfma_f32_16x16x32_bf16 v[36:39], v[148:151], v[172:175], v[36:39]
	v_mfma_f32_16x16x32_bf16 v[32:35], v[156:159], v[172:175], v[32:35]
	v_mfma_f32_16x16x32_bf16 v[20:23], v[148:151], v[180:183], v[20:23]
	v_mfma_f32_16x16x32_bf16 v[16:19], v[156:159], v[180:183], v[16:19]
	v_mfma_f32_16x16x32_bf16 v[4:7], v[148:151], v[188:191], v[4:7]
	v_mfma_f32_16x16x32_bf16 v[0:3], v[156:159], v[188:191], v[0:3]
	s_barrier
	s_add_i32 s77, s77, 2
	s_add_u32 s8, s8, 0x800000
	s_addc_u32 s9, s9, 0
	s_add_u32 s67, s67, 0x100
	s_addc_u32 s76, s76, 0
	s_cmp_gt_u32 s77, 13
	s_cbranch_scc0 .LBB0_480
	s_and_b64 vcc, exec, s[26:27]
	s_cbranch_vccz .LBB0_483
	s_barrier
